# GEMM k-loop: per-lane parts of the four top-group DMA source pointers folded once per tile (5 fewer VALU per k-iteration)
# speedup vs baseline: 1.0064x; 1.0019x over previous
.LBB0_637:
	s_and_b64 s[2:3], s[8:9], exec
	v_readlane_b32 s2, v255, 26
	v_readlane_b32 s4, v255, 30
	v_readlane_b32 s3, v255, 27
	v_readlane_b32 s5, v255, 31
	s_cselect_b32 s24, s5, s3
	s_cselect_b32 s28, s4, s2
	v_readlane_b32 s2, v255, 24
	v_readlane_b32 s4, v255, 32
	v_readlane_b32 s3, v255, 25
	v_readlane_b32 s5, v255, 33
	s_cselect_b32 s29, s5, s3
	s_cselect_b32 s34, s4, s2
	v_readlane_b32 s2, v255, 23
	v_readlane_b32 s3, v255, 43
	s_cselect_b32 s14, s3, s2
	v_readlane_b32 s2, v255, 39
	s_cselect_b32 s39, s2, 0
	v_readlane_b32 s2, v255, 18
	v_readlane_b32 s3, v255, 40
	s_cselect_b32 s44, s3, s2
	s_lshl_b32 s45, s15, 8
	s_mul_i32 s2, s15, 0xfe
	s_add_i32 s45, s45, s39
	s_lshl_b32 s6, s47, 8
	s_add_i32 s4, s2, -1
	s_cmp_eq_u32 s44, 7
	s_cselect_b64 vcc, -1, 0
	s_and_b64 s[2:3], vcc, exec
	s_cselect_b32 s2, 0, s45
	s_cselect_b32 s40, s4, 0
	s_ashr_i32 s3, s2, 31
	v_mov_b32_e32 v175, v163
	s_mul_i32 s3, s3, s14
	s_mul_hi_u32 s4, s2, s14
	s_ashr_i32 s7, s6, 31
	s_add_i32 s3, s4, s3
	s_waitcnt vmcnt(1)
	v_ashrrev_i32_e32 v10, 6, v175
	s_waitcnt vmcnt(0)
	v_bfe_u32 v14, v175, 3, 3
	s_mul_i32 s2, s2, s14
	s_mul_i32 s4, s7, s14
	s_mul_hi_u32 s5, s6, s14
	v_lshl_or_b32 v6, v10, 5, v14
	s_add_i32 s5, s5, s4
	v_and_b32_e32 v0, 63, v175
	s_lshl_b64 s[2:3], s[2:3], 1
	s_mul_i32 s4, s6, s14
	s_add_u32 s2, s28, s2
	v_lshlrev_b32_e32 v176, 4, v0
	v_add_u32_e32 v0, s40, v6
	s_addc_u32 s3, s24, s3
	s_lshl_b64 s[4:5], s[4:5], 1
	v_med3_i32 v0, v0, 0, v211
	s_add_u32 s4, s34, s4
	v_cndmask_b32_e32 v0, v6, v0, vcc
	s_addc_u32 s5, s29, s5
	v_bfe_u32 v223, v175, 4, 2
	v_mad_u64_u32 v[166:167], s[28:29], v0, s14, 0
	v_xor_b32_e32 v4, v223, v175
	v_ashrrev_i32_e32 v2, 31, v0
	v_mov_b32_e32 v0, v167
	v_mad_u64_u32 v[2:3], s[28:29], v2, s14, v[0:1]
	v_lshlrev_b32_e32 v0, 3, v4
	v_lshlrev_b32_e32 v15, 2, v10
	v_and_b32_e32 v0, 56, v0
	v_lshlrev_b32_e32 v177, 12, v10
	v_lshlrev_b32_e32 v130, 1, v0
	v_ashrrev_i32_e32 v0, 31, v10
	v_or_b32_e32 v17, v176, v177
	v_or_b32_e32 v18, 1, v15
	v_and_b32_e32 v174, 3, v10
	v_mul_lo_u32 v16, v0, s14
	v_readfirstlane_b32 s15, v17
	v_add_u32_e32 v0, 0x8000, v17
	v_lshl_or_b32 v10, v18, 3, v14
	v_mov_b32_e32 v167, v2
	v_mad_u64_u32 v[168:169], s[28:29], v6, s14, 0
	s_mov_b32 m0, s15
	v_readfirstlane_b32 s15, v0
	v_add_u32_e32 v0, s40, v10
	v_lshl_add_u64 v[2:3], v[166:167], 1, s[2:3]
	v_mov_b32_e32 v131, v1
	v_add_u32_e32 v169, v169, v16
	v_med3_i32 v0, v0, 0, v211
	v_lshl_add_u64 v[4:5], v[2:3], 0, v[130:131]
	v_lshl_add_u64 v[6:7], v[168:169], 1, s[4:5]
	v_cndmask_b32_e32 v0, v10, v0, vcc
	v_lshl_add_u64 v[8:9], v[6:7], 0, v[130:131]
	global_load_lds_dwordx4 v[4:5], off
	s_mov_b32 m0, s15
	v_lshrrev_b32_e32 v4, 1, v10
	v_mad_u64_u32 v[170:171], s[28:29], v0, s14, 0
	global_load_lds_dwordx4 v[8:9], off
	v_xor_b32_e32 v8, v4, v175
	v_ashrrev_i32_e32 v4, 31, v0
	v_mov_b32_e32 v0, v171
	v_mad_u64_u32 v[4:5], s[28:29], v4, s14, v[0:1]
	v_lshlrev_b32_e32 v0, 3, v8
	v_lshlrev_b32_e32 v178, 10, v18
	v_mov_b32_e32 v171, v4
	v_and_b32_e32 v0, 56, v0
	v_mad_u64_u32 v[172:173], s[28:29], v10, s14, 0
	v_or_b32_e32 v18, v176, v178
	v_lshl_add_u64 v[4:5], v[170:171], 1, s[2:3]
	v_lshlrev_b32_e32 v132, 1, v0
	v_mov_b32_e32 v133, v1
	v_add_u32_e32 v173, v173, v16
	v_readfirstlane_b32 s15, v18
	v_add_u32_e32 v0, 0x8000, v18
	v_lshl_add_u64 v[8:9], v[4:5], 0, v[132:133]
	v_lshl_add_u64 v[10:11], v[172:173], 1, s[4:5]
	s_mov_b32 m0, s15
	v_readfirstlane_b32 s15, v0
	s_waitcnt lgkmcnt(0)
	v_lshl_add_u64 v[12:13], v[10:11], 0, v[132:133]
	global_load_lds_dwordx4 v[8:9], off
	s_mov_b32 m0, s15
	v_or_b32_e32 v19, 2, v15
	global_load_lds_dwordx4 v[12:13], off
	v_lshl_or_b32 v12, v19, 3, v14
	v_add_u32_e32 v0, s40, v12
	v_med3_i32 v0, v0, 0, v211
	v_cndmask_b32_e32 v0, v12, v0, vcc
	v_lshrrev_b32_e32 v8, 1, v12
	v_mad_u64_u32 v[154:155], s[28:29], v0, s14, 0
	v_xor_b32_e32 v13, v8, v175
	v_ashrrev_i32_e32 v8, 31, v0
	v_mov_b32_e32 v0, v155
	v_mad_u64_u32 v[8:9], s[28:29], v8, s14, v[0:1]
	v_lshlrev_b32_e32 v0, 3, v13
	v_lshlrev_b32_e32 v179, 10, v19
	v_mov_b32_e32 v155, v8
	v_and_b32_e32 v0, 56, v0
	v_or_b32_e32 v19, v176, v179
	v_lshl_add_u64 v[8:9], v[154:155], 1, s[2:3]
	v_lshlrev_b32_e32 v0, 1, v0
	v_readfirstlane_b32 s15, v19
	v_lshl_add_u64 v[8:9], v[8:9], 0, v[0:1]
	v_mad_u64_u32 v[156:157], s[28:29], v12, s14, 0
	s_mov_b32 m0, s15
	v_add_u32_e32 v157, v157, v16
	global_load_lds_dwordx4 v[8:9], off
	v_add_u32_e32 v8, 0x8000, v19
	v_lshl_add_u64 v[12:13], v[156:157], 1, s[4:5]
	v_readfirstlane_b32 s15, v8
	v_lshl_add_u64 v[12:13], v[12:13], 0, v[0:1]
	s_mov_b32 m0, s15
	v_or_b32_e32 v15, 3, v15
	global_load_lds_dwordx4 v[12:13], off
	v_lshl_or_b32 v12, v15, 3, v14
	v_add_u32_e32 v8, s40, v12
	v_med3_i32 v8, v8, 0, v211
	v_cndmask_b32_e32 v8, v12, v8, vcc
	v_lshrrev_b32_e32 v9, 1, v12
	v_mad_u64_u32 v[158:159], s[28:29], v8, s14, 0
	v_xor_b32_e32 v13, v9, v175
	v_ashrrev_i32_e32 v9, 31, v8
	v_mov_b32_e32 v8, v159
	v_mad_u64_u32 v[8:9], s[28:29], v9, s14, v[8:9]
	v_lshlrev_b32_e32 v13, 3, v13
	v_lshlrev_b32_e32 v180, 10, v15
	v_mov_b32_e32 v159, v8
	v_and_b32_e32 v13, 56, v13
	v_or_b32_e32 v14, v176, v180
	v_lshl_add_u64 v[8:9], v[158:159], 1, s[2:3]
	v_lshlrev_b32_e32 v160, 1, v13
	v_mov_b32_e32 v161, v1
	v_readfirstlane_b32 s15, v14
	v_lshl_add_u64 v[8:9], v[8:9], 0, v[160:161]
	v_mad_u64_u32 v[164:165], s[28:29], v12, s14, 0
	s_mov_b32 m0, s15
	v_add_u32_e32 v165, v165, v16
	global_load_lds_dwordx4 v[8:9], off
	v_add_u32_e32 v8, 0x8000, v14
	s_cmpk_gt_u32 s14, 0x7f
	v_lshl_add_u64 v[12:13], v[164:165], 1, s[4:5]
	v_readfirstlane_b32 s15, v8
	s_cselect_b32 s34, 0x80, 0
	v_add_u32_e32 v8, 0x10000, v17
	v_lshl_add_u64 v[12:13], v[12:13], 0, v[160:161]
	s_mov_b32 m0, s15
	v_lshl_add_u64 v[2:3], v[2:3], 0, s[34:35]
	v_readfirstlane_b32 s15, v8
	global_load_lds_dwordx4 v[12:13], off
	v_lshl_add_u64 v[2:3], v[2:3], 0, v[130:131]
	s_mov_b32 m0, s15
	v_mov_b32_e32 v127, 0
	v_mov_b32_e32 v128, 0
	v_mov_b32_e32 v129, 0
	v_mov_b32_e32 v122, 0
	v_mov_b32_e32 v123, 0
	v_mov_b32_e32 v124, 0
	v_mov_b32_e32 v125, 0
	v_mov_b32_e32 v118, 0
	v_mov_b32_e32 v119, 0
	v_mov_b32_e32 v120, 0
	v_mov_b32_e32 v121, 0
	v_mov_b32_e32 v114, 0
	v_mov_b32_e32 v115, 0
	v_mov_b32_e32 v116, 0
	v_mov_b32_e32 v117, 0
	v_mov_b32_e32 v110, 0
	v_mov_b32_e32 v111, 0
	v_mov_b32_e32 v112, 0
	v_mov_b32_e32 v113, 0
	v_mov_b32_e32 v106, 0
	v_mov_b32_e32 v107, 0
	v_mov_b32_e32 v108, 0
	v_mov_b32_e32 v109, 0
	v_mov_b32_e32 v102, 0
	v_mov_b32_e32 v103, 0
	v_mov_b32_e32 v104, 0
	v_mov_b32_e32 v105, 0
	v_mov_b32_e32 v98, 0
	v_mov_b32_e32 v99, 0
	v_mov_b32_e32 v100, 0
	v_mov_b32_e32 v101, 0
	v_mov_b32_e32 v94, 0
	v_mov_b32_e32 v95, 0
	v_mov_b32_e32 v96, 0
	v_mov_b32_e32 v97, 0
	v_mov_b32_e32 v90, 0
	v_mov_b32_e32 v91, 0
	v_mov_b32_e32 v92, 0
	v_mov_b32_e32 v93, 0
	v_mov_b32_e32 v86, 0
	v_mov_b32_e32 v87, 0
	v_mov_b32_e32 v88, 0
	v_mov_b32_e32 v89, 0
	v_mov_b32_e32 v82, 0
	v_mov_b32_e32 v83, 0
	v_mov_b32_e32 v84, 0
	v_mov_b32_e32 v85, 0
	v_mov_b32_e32 v78, 0
	v_mov_b32_e32 v79, 0
	v_mov_b32_e32 v80, 0
	v_mov_b32_e32 v81, 0
	v_mov_b32_e32 v74, 0
	v_mov_b32_e32 v75, 0
	v_mov_b32_e32 v76, 0
	v_mov_b32_e32 v77, 0
	v_mov_b32_e32 v70, 0
	v_mov_b32_e32 v71, 0
	v_mov_b32_e32 v72, 0
	v_mov_b32_e32 v73, 0
	v_mov_b32_e32 v66, 0
	v_mov_b32_e32 v67, 0
	v_mov_b32_e32 v68, 0
	v_mov_b32_e32 v69, 0
	v_mov_b32_e32 v62, 0
	v_mov_b32_e32 v63, 0
	v_mov_b32_e32 v64, 0
	v_mov_b32_e32 v65, 0
	v_mov_b32_e32 v58, 0
	v_mov_b32_e32 v59, 0
	v_mov_b32_e32 v60, 0
	v_mov_b32_e32 v61, 0
	v_mov_b32_e32 v54, 0
	v_mov_b32_e32 v55, 0
	v_mov_b32_e32 v56, 0
	v_mov_b32_e32 v57, 0
	v_mov_b32_e32 v50, 0
	v_mov_b32_e32 v51, 0
	v_mov_b32_e32 v52, 0
	v_mov_b32_e32 v53, 0
	v_mov_b32_e32 v46, 0
	v_mov_b32_e32 v47, 0
	v_mov_b32_e32 v48, 0
	v_mov_b32_e32 v49, 0
	v_mov_b32_e32 v42, 0
	v_mov_b32_e32 v43, 0
	v_mov_b32_e32 v44, 0
	v_mov_b32_e32 v45, 0
	v_mov_b32_e32 v34, 0
	v_mov_b32_e32 v35, 0
	v_mov_b32_e32 v36, 0
	v_mov_b32_e32 v37, 0
	v_mov_b32_e32 v30, 0
	v_mov_b32_e32 v31, 0
	v_mov_b32_e32 v32, 0
	v_mov_b32_e32 v33, 0
	v_mov_b32_e32 v38, 0
	v_mov_b32_e32 v39, 0
	v_mov_b32_e32 v40, 0
	v_mov_b32_e32 v41, 0
	v_mov_b32_e32 v26, 0
	v_mov_b32_e32 v27, 0
	v_mov_b32_e32 v28, 0
	v_mov_b32_e32 v29, 0
	v_mov_b32_e32 v22, 0
	v_mov_b32_e32 v23, 0
	v_mov_b32_e32 v24, 0
	v_mov_b32_e32 v25, 0
	v_mov_b32_e32 v19, 0
	v_mov_b32_e32 v20, 0
	v_mov_b32_e32 v21, 0
	v_mov_b32_e32 v14, 0
	v_mov_b32_e32 v15, 0
	v_mov_b32_e32 v16, 0
	v_mov_b32_e32 v12, 0
	v_mov_b32_e32 v13, 0
	s_waitcnt vmcnt(0)
	s_waitcnt vmcnt(0) lgkmcnt(0)
	s_barrier
	global_load_lds_dwordx4 v[2:3], off
	v_add_u32_e32 v2, 0x18000, v17
	v_lshl_add_u64 v[6:7], v[6:7], 0, s[34:35]
	v_readfirstlane_b32 s15, v2
	v_lshl_add_u64 v[6:7], v[6:7], 0, v[130:131]
	s_mov_b32 m0, s15
	v_lshl_add_u64 v[2:3], v[4:5], 0, s[34:35]
	global_load_lds_dwordx4 v[6:7], off
	v_add_u32_e32 v6, 0x10000, v18
	v_lshl_add_u64 v[2:3], v[2:3], 0, v[132:133]
	v_readfirstlane_b32 s15, v6
	s_mov_b32 m0, s15
	v_lshl_add_u64 v[4:5], v[10:11], 0, s[34:35]
	global_load_lds_dwordx4 v[2:3], off
	v_add_u32_e32 v2, 0x18000, v18
	v_lshl_add_u64 v[4:5], v[4:5], 0, v[132:133]
	v_readfirstlane_b32 s15, v2
	s_mov_b32 m0, s15
	v_and_b32_e32 v134, 15, v175
	global_load_lds_dwordx4 v[4:5], off
	v_ashrrev_i32_e32 v2, 1, v175
	s_movk_i32 s15, 0xff80
	v_mov_b32_e32 v5, 0
	v_and_or_b32 v225, v2, s15, v134
	v_lshlrev_b32_e32 v224, 6, v174
	s_cmp_lt_u32 s14, 64
	v_readlane_b32 s51, v255, 37
	v_readlane_b32 s52, v255, 38
	s_cbranch_scc1 .Lgemm_skip_zero_a
	v_lshrrev_b32_e32 v10, 1, v134
	v_or_b32_e32 v2, v224, v134
	v_lshlrev_b32_e32 v182, 7, v2
	v_xor_b32_e32 v2, v223, v10
	v_lshlrev_b32_e32 v181, 7, v225
	v_lshlrev_b32_e32 v183, 4, v2
	v_or_b32_e32 v11, v181, v183
	v_or_b32_e32 v244, v182, v183
	v_lshl_add_u64 v[2:3], s[4:5], 0, v[132:133]
	v_lshl_add_u64 v[4:5], s[2:3], 0, v[132:133]
	v_lshl_add_u64 v[6:7], s[4:5], 0, v[130:131]
	v_lshl_add_u64 v[8:9], s[2:3], 0, v[130:131]
	ds_read_b128 v[150:153], v11
	ds_read_b128 v[146:149], v11 offset:2048
	ds_read_b128 v[142:145], v244 offset:32768
	ds_read_b128 v[138:141], v244 offset:34816
	ds_read_b128 v[134:137], v244 offset:36864
	ds_read_b128 v[200:203], v11 offset:4096
	ds_read_b128 v[130:133], v244 offset:38912
	ds_read_b128 v[236:239], v11 offset:6144
	s_lshr_b32 s14, s14, 6
	v_bitop3_b32 v10, v223, v10, 4 bitop3:0x36
	v_mov_b32_e32 v126, 0
	s_add_i32 s15, s14, -1
	v_lshlrev_b32_e32 v184, 4, v10
	v_lshl_add_u64 v[166:167], v[166:167], 1, v[8:9]
	v_lshl_add_u64 v[168:169], v[168:169], 1, v[6:7]
	v_lshl_add_u64 v[170:171], v[170:171], 1, v[4:5]
	v_lshl_add_u64 v[172:173], v[172:173], 1, v[2:3]
	s_mov_b32 s24, 0
	s_mov_b32 s28, 0
	v_mov_b32_e32 v161, v1
	v_lshl_add_u64 v[154:155], v[154:155], 1, v[0:1]
	v_lshl_add_u64 v[156:157], v[156:157], 1, v[0:1]
	v_lshl_add_u64 v[158:159], v[158:159], 1, v[160:161]
	v_lshl_add_u64 v[164:165], v[164:165], 1, v[160:161]
	v_readfirstlane_b32 s100, v179
	v_readfirstlane_b32 s101, v180
	v_readfirstlane_b32 s32, v178
	v_readfirstlane_b32 s41, v177
	s_lshl_b32 s32, s32, 16
	s_or_b32 s32, s32, s41
	v_mov_b32_e32 v18, v126
	v_mov_b32_e32 v17, v126
	v_mov_b32_e32 v10, v126
	v_mov_b32_e32 v11, v126
	v_mov_b32_e32 v6, v126
	v_mov_b32_e32 v7, v126
	v_mov_b32_e32 v8, v126
	v_mov_b32_e32 v9, v126
	v_mov_b32_e32 v2, v126
	v_mov_b32_e32 v3, v126
	v_mov_b32_e32 v4, v126
	v_mov_b32_e32 v5, v126
.LBB0_639:
	s_add_i32 s41, s28, 1
	s_cmp_lt_u32 s41, s14
	s_cselect_b32 s29, s41, s28
	s_and_b32 s46, s24, 0x10000
	s_lshl_b32 s34, s29, 6
	s_xor_b32 s50, s46, 0x10000
	s_lshl_b64 s[42:43], s[34:35], 1
	s_add_u32 s48, s2, s42
	s_addc_u32 s49, s3, s43
	s_add_u32 s42, s4, s42
	v_add_u32_e32 v185, s46, v181
	s_waitcnt lgkmcnt(5)
	v_mfma_f32_16x16x32_bf16 v[126:129], v[142:145], v[150:153], v[126:129]
	s_addc_u32 s43, s5, s43
	v_lshl_add_u64 v[186:187], v[154:155], 0, s[48:49]
	v_add_u32_e32 v227, v185, v183
	v_mfma_f32_16x16x32_bf16 v[110:113], v[142:145], v[146:149], v[110:113]
	v_lshl_add_u64 v[240:241], v[156:157], 0, s[42:43]
	s_add_i32 m0, s50, s100
	s_waitcnt lgkmcnt(4)
	v_mfma_f32_16x16x32_bf16 v[122:125], v[138:141], v[150:153], v[122:125]
	s_add_i32 s28, s28, 2
	s_min_i32 s28, s28, s15
	s_lshl_b32 s28, s28, 6
	v_mfma_f32_16x16x32_bf16 v[106:109], v[138:141], v[146:149], v[106:109]
	global_load_lds_dwordx4 v[186:187], off
	s_add_i32 m0, m0, 0x8000
	s_waitcnt lgkmcnt(3)
	v_mfma_f32_16x16x32_bf16 v[118:121], v[134:137], v[150:153], v[118:121]
	v_lshl_add_u64 v[244:245], v[158:159], 0, s[48:49]
	v_lshl_add_u64 v[246:247], v[164:165], 0, s[42:43]
	v_mfma_f32_16x16x32_bf16 v[102:105], v[134:137], v[146:149], v[102:105]
	global_load_lds_dwordx4 v[240:241], off
	s_add_i32 m0, s50, s101
	s_waitcnt lgkmcnt(1)
	v_mfma_f32_16x16x32_bf16 v[114:117], v[130:133], v[150:153], v[114:117]
	ds_read_b128 v[150:153], v227 offset:8192
	v_mfma_f32_16x16x32_bf16 v[98:101], v[130:133], v[146:149], v[98:101]
	ds_read_b128 v[146:149], v227 offset:10240
	v_mfma_f32_16x16x32_bf16 v[94:97], v[142:145], v[200:203], v[94:97]
	v_mfma_f32_16x16x32_bf16 v[90:93], v[138:141], v[200:203], v[90:93]
	global_load_lds_dwordx4 v[244:245], off
	s_add_i32 m0, m0, 0x8000
	v_mfma_f32_16x16x32_bf16 v[86:89], v[134:137], v[200:203], v[86:89]
	v_mfma_f32_16x16x32_bf16 v[82:85], v[130:133], v[200:203], v[82:85]
	ds_read_b128 v[200:203], v227 offset:12288
	v_bitop3_b32 v243, s24, v182, v212 bitop3:0xce
	s_waitcnt lgkmcnt(3)
	v_mfma_f32_16x16x32_bf16 v[78:81], v[142:145], v[236:239], v[78:81]
	global_load_lds_dwordx4 v[246:247], off
	v_add_u32_e32 v233, v243, v183
	v_mfma_f32_16x16x32_bf16 v[74:77], v[138:141], v[236:239], v[74:77]
	v_mfma_f32_16x16x32_bf16 v[70:73], v[134:137], v[236:239], v[70:73]
	v_or_b32_e32 v228, s46, v182
	s_ashr_i32 s29, s28, 31
	v_mfma_f32_16x16x32_bf16 v[66:69], v[130:133], v[236:239], v[66:69]
	ds_read_b128 v[236:239], v227 offset:14336
	s_waitcnt lgkmcnt(3)
	v_mfma_f32_16x16x32_bf16 v[62:65], v[142:145], v[150:153], v[62:65]
	v_add3_u32 v234, s50, v181, v183
	v_add_u32_e32 v228, v228, v184
	v_mfma_f32_16x16x32_bf16 v[58:61], v[138:141], v[150:153], v[58:61]
	v_add_u32_e32 v229, v185, v184
	v_mfma_f32_16x16x32_bf16 v[54:57], v[134:137], v[150:153], v[54:57]
	v_mfma_f32_16x16x32_bf16 v[50:53], v[130:133], v[150:153], v[50:53]
	ds_read_b128 v[150:153], v229
	s_waitcnt lgkmcnt(3)
	v_mfma_f32_16x16x32_bf16 v[46:49], v[142:145], v[146:149], v[46:49]
	v_mfma_f32_16x16x32_bf16 v[42:45], v[138:141], v[146:149], v[42:45]
	v_mfma_f32_16x16x32_bf16 v[34:37], v[134:137], v[146:149], v[34:37]
	v_mfma_f32_16x16x32_bf16 v[30:33], v[130:133], v[146:149], v[30:33]
	ds_read_b128 v[146:149], v229 offset:2048
	s_waitcnt lgkmcnt(3)
	v_mfma_f32_16x16x32_bf16 v[38:41], v[142:145], v[200:203], v[38:41]
	s_waitcnt lgkmcnt(2)
	v_mfma_f32_16x16x32_bf16 v[14:17], v[142:145], v[236:239], v[14:17]
	ds_read_b128 v[142:145], v228 offset:32768
	v_mfma_f32_16x16x32_bf16 v[26:29], v[138:141], v[200:203], v[26:29]
	v_mfma_f32_16x16x32_bf16 v[10:13], v[138:141], v[236:239], v[10:13]
	ds_read_b128 v[138:141], v228 offset:34816
	v_mfma_f32_16x16x32_bf16 v[22:25], v[134:137], v[200:203], v[22:25]
	v_mfma_f32_16x16x32_bf16 v[6:9], v[134:137], v[236:239], v[6:9]
	ds_read_b128 v[134:137], v228 offset:36864
	v_mfma_f32_16x16x32_bf16 v[18:21], v[130:133], v[200:203], v[18:21]
	ds_read_b128 v[200:203], v229 offset:4096
	v_mfma_f32_16x16x32_bf16 v[2:5], v[130:133], v[236:239], v[2:5]
	ds_read_b128 v[130:133], v228 offset:38912
	ds_read_b128 v[236:239], v229 offset:6144
	s_waitcnt lgkmcnt(5)
	v_mfma_f32_16x16x32_bf16 v[126:129], v[142:145], v[150:153], v[126:129]
	v_mfma_f32_16x16x32_bf16 v[110:113], v[142:145], v[146:149], v[110:113]
	s_waitcnt lgkmcnt(4)
	v_mfma_f32_16x16x32_bf16 v[122:125], v[138:141], v[150:153], v[122:125]
	v_mfma_f32_16x16x32_bf16 v[106:109], v[138:141], v[146:149], v[106:109]
	s_waitcnt lgkmcnt(3)
	v_mfma_f32_16x16x32_bf16 v[118:121], v[134:137], v[150:153], v[118:121]
	v_mfma_f32_16x16x32_bf16 v[102:105], v[134:137], v[146:149], v[102:105]
	s_waitcnt lgkmcnt(1)
	v_mfma_f32_16x16x32_bf16 v[114:117], v[130:133], v[150:153], v[114:117]
	ds_read_b128 v[150:153], v229 offset:8192
	v_mfma_f32_16x16x32_bf16 v[98:101], v[130:133], v[146:149], v[98:101]
	ds_read_b128 v[146:149], v229 offset:10240
	v_mfma_f32_16x16x32_bf16 v[94:97], v[142:145], v[200:203], v[94:97]
	v_mfma_f32_16x16x32_bf16 v[90:93], v[138:141], v[200:203], v[90:93]
	v_mfma_f32_16x16x32_bf16 v[86:89], v[134:137], v[200:203], v[86:89]
	v_mfma_f32_16x16x32_bf16 v[82:85], v[130:133], v[200:203], v[82:85]
	ds_read_b128 v[200:203], v229 offset:12288
	s_waitcnt lgkmcnt(3)
	v_mfma_f32_16x16x32_bf16 v[78:81], v[142:145], v[236:239], v[78:81]
	v_mfma_f32_16x16x32_bf16 v[74:77], v[138:141], v[236:239], v[74:77]
	v_mfma_f32_16x16x32_bf16 v[70:73], v[134:137], v[236:239], v[70:73]
	s_lshl_b64 s[28:29], s[28:29], 1
	s_and_b32 m0, s32, 0xffff
	v_mfma_f32_16x16x32_bf16 v[66:69], v[130:133], v[236:239], v[66:69]
	ds_read_b128 v[236:239], v229 offset:14336
	s_add_i32 m0, m0, s46
	s_waitcnt lgkmcnt(3)
	v_mfma_f32_16x16x32_bf16 v[62:65], v[142:145], v[150:153], v[62:65]
	v_mfma_f32_16x16x32_bf16 v[58:61], v[138:141], v[150:153], v[58:61]
	v_mfma_f32_16x16x32_bf16 v[54:57], v[134:137], v[150:153], v[54:57]
	v_mfma_f32_16x16x32_bf16 v[50:53], v[130:133], v[150:153], v[50:53]
	s_waitcnt vmcnt(0) lgkmcnt(0)
	s_barrier
	ds_read_b128 v[150:153], v234
	v_mfma_f32_16x16x32_bf16 v[46:49], v[142:145], v[146:149], v[46:49]
	v_lshl_add_u64 v[240:241], v[166:167], 0, s[28:29]
	v_lshl_add_u64 v[244:245], v[168:169], 0, s[28:29]
	global_load_lds_dwordx4 v[240:241], off
	s_add_i32 m0, m0, 0x8000
	v_mfma_f32_16x16x32_bf16 v[42:45], v[138:141], v[146:149], v[42:45]
	v_mfma_f32_16x16x32_bf16 v[34:37], v[134:137], v[146:149], v[34:37]
	global_load_lds_dwordx4 v[244:245], off
	s_lshr_b32 m0, s32, 16
	v_mfma_f32_16x16x32_bf16 v[30:33], v[130:133], v[146:149], v[30:33]
	ds_read_b128 v[146:149], v234 offset:2048
	v_lshl_add_u64 v[246:247], v[170:171], 0, s[28:29]
	v_lshl_add_u64 v[242:243], v[172:173], 0, s[28:29]
	s_add_i32 m0, m0, s46
	v_mfma_f32_16x16x32_bf16 v[38:41], v[142:145], v[200:203], v[38:41]
	v_mfma_f32_16x16x32_bf16 v[14:17], v[142:145], v[236:239], v[14:17]
	ds_read_b128 v[142:145], v233 offset:32768
	global_load_lds_dwordx4 v[246:247], off
	s_add_i32 m0, m0, 0x8000
	v_mfma_f32_16x16x32_bf16 v[26:29], v[138:141], v[200:203], v[26:29]
	v_mfma_f32_16x16x32_bf16 v[10:13], v[138:141], v[236:239], v[10:13]
	ds_read_b128 v[138:141], v233 offset:34816
	global_load_lds_dwordx4 v[242:243], off
	v_mfma_f32_16x16x32_bf16 v[22:25], v[134:137], v[200:203], v[22:25]
	v_mfma_f32_16x16x32_bf16 v[6:9], v[134:137], v[236:239], v[6:9]
	ds_read_b128 v[134:137], v233 offset:36864
	v_mfma_f32_16x16x32_bf16 v[18:21], v[130:133], v[200:203], v[18:21]
	ds_read_b128 v[200:203], v234 offset:4096
	v_mfma_f32_16x16x32_bf16 v[2:5], v[130:133], v[236:239], v[2:5]
	ds_read_b128 v[130:133], v233 offset:38912
	ds_read_b128 v[236:239], v234 offset:6144
	s_add_i32 s24, s24, 0x10000
	s_cmp_eq_u32 s14, s41
	s_mov_b32 s28, s41
	s_cbranch_scc0 .LBB0_639
